# GEMM tile start: accumulator zeroing with v_mov_b64 pairs instead of 127 v_mov_b32 (gate/up and in-proj instances)
# baseline (speedup 1.0000x reference)
;     __device__ __forceinline__ void prefetch(const Unit& u, PG8_LAS unsigned char* slot, int tid, int wid) const { if (f.on) xslot_fetch(f.st + 8 * (u.pm * BM), f.c1 + u.pn * BM, f.c2 + u.pn * BM, slot, tid, wid); }
;     __device__ __forceinline__ void prefetch(const Unit& u, PG8_LAS unsigned char* slot, int tid, int wid) const { xslot_fetch(f.st + 8 * (u.pm * BM), f.c1 + u.pn * BM, f.c2 + u.pn * BM, slot, tid, wid); }
;     __device__ __forceinline__ void prefetch(const Unit& u, PG8_LAS unsigned char* slot, int tid, int wid) const { if (st_prev) xslot_fetch(st_prev + 8 * (u.pm * BM), gp + u.pn * BM, bp + u.pn * BM, slot, tid, wid); }
; template <class Epi, class Sched, bool ALIGN_EPI = false, bool SP2 = false>
; __device__ __forceinline__ void gemm_phase(PG8_LAS unsigned char* lds, const Gemm g, const Sched& S, const Epi& E) {
;     ...
;         const bool has_next = S.next(ui + 1, nxt);
;         const char* nA = has_next ? (const char*)g.A + (size_t)nxt.pm * tstep : cA; const char* nB = has_next ? (const char*)g.Bt + (size_t)nxt.pn * tstep : cB;
;         for (int t = 0; t < nt; t += 2) {
;             const bool last = (t == nt - 2);
;             const char* a1 = cA + (size_t)(t + 1) * kstep;
;             const char* a2 = last ? nA : cA + (size_t)(t + 2) * kstep; const char* b2 = last ? nB : cB + (size_t)(t + 2) * kstep;
;             const char* a3 = a2 + kstep; const char* b3 = b2 + kstep;
;             if (last) E.preload(pre, cur, wr, wc, fr, fq);
;             if (last && has_next) { S.a_ready(nxt); E.prefetch(nxt, lds + XSLOT_OFF + ((ui + 1) & 1) * XSLOT_BYTES, tid, wid); }
;     ...
;         for (int a = 0; a < 2; ++a)
; #pragma unroll
;             for (int b = 0; b < 2; ++b)
; #pragma unroll
;                 for (int m = 0; m < 4; ++m)
; #pragma unroll
;                     for (int n = 0; n < 2; ++n) acc[a][b][m][n] = (f32x4){0.f, 0.f, 0.f, 0.f};
;         cur = nxt; cA = nA; cB = nB; ++ui;
.LBB0_453:
	s_ashr_i32 s17, s16, 31
	s_lshl_b64 s[2:3], s[16:17], 19
	v_readlane_b32 s18, v250, 4
	v_readlane_b32 s19, v250, 5
	s_add_u32 s18, s18, s2
	s_addc_u32 s19, s19, s3
	s_and_b64 s[2:3], s[40:41], exec
	s_cselect_b32 s17, s19, s27
	s_cselect_b32 s46, s18, s26
	s_ashr_i32 s15, s14, 31
	s_lshl_b64 s[2:3], s[14:15], 19
	s_add_u32 s20, s28, s2
	s_addc_u32 s21, s29, s3
	s_and_b64 s[2:3], s[40:41], exec
	s_cselect_b32 s15, s21, s25
	s_cselect_b32 s47, s20, s24
	s_bitcmp1_b32 s43, 0
	s_cselect_b32 s2, 0x2800, 0
	s_add_i32 s48, s2, 0
	s_lshl_b32 s2, s16, 11
	s_lshl_b32 s50, s14, 8
	s_ashr_i32 s3, s2, 31
	s_ashr_i32 s51, s50, 31
	v_lshl_add_u64 v[116:117], s[2:3], 2, v[170:171]
	s_lshl_b64 s[2:3], s[50:51], 2
	v_lshl_add_u64 v[4:5], v[172:173], 0, s[2:3]
	v_lshl_add_u64 v[6:7], v[174:175], 0, s[2:3]
	s_movk_i32 s2, 0xfc00
	s_add_i32 s48, s48, 0x20000
	s_mov_b32 s3, -1
	v_lshl_add_u64 v[6:7], v[6:7], 0, s[2:3]
	s_add_u32 s2, s26, 0x40080
	s_addc_u32 s3, s27, 0
	v_cndmask_b32_e64 v118, v6, v4, s[38:39]
	s_add_u32 s49, s24, 0x100
	v_mov_b32_e32 v4, 0
	v_cndmask_b32_e64 v119, v7, v5, s[38:39]
	s_addc_u32 s50, s25, 0
	s_mov_b32 s51, -2
	v_mov_b32_e32 v5, v4
	v_mov_b64_e32 v[6:7], 0
	v_mov_b64_e32 v[8:9], 0
	v_mov_b64_e32 v[10:11], 0
	v_mov_b64_e32 v[12:13], 0
	v_mov_b64_e32 v[14:15], 0
	v_mov_b64_e32 v[16:17], 0
	v_mov_b64_e32 v[18:19], 0
	v_mov_b64_e32 v[20:21], 0
	v_mov_b64_e32 v[22:23], 0
	v_mov_b64_e32 v[24:25], 0
	v_mov_b64_e32 v[26:27], 0
	v_mov_b64_e32 v[28:29], 0
	v_mov_b64_e32 v[30:31], 0
	v_mov_b64_e32 v[32:33], 0
	v_mov_b64_e32 v[34:35], 0
	v_mov_b64_e32 v[36:37], 0
	v_mov_b64_e32 v[38:39], 0
	v_mov_b64_e32 v[40:41], 0
	v_mov_b64_e32 v[42:43], 0
	v_mov_b64_e32 v[44:45], 0
	v_mov_b64_e32 v[46:47], 0
	v_mov_b64_e32 v[48:49], 0
	v_mov_b64_e32 v[50:51], 0
	v_mov_b64_e32 v[52:53], 0
	v_mov_b64_e32 v[54:55], 0
	v_mov_b64_e32 v[56:57], 0
	v_mov_b64_e32 v[58:59], 0
	v_mov_b64_e32 v[60:61], 0
	v_mov_b64_e32 v[62:63], 0
	v_mov_b64_e32 v[64:65], 0
	v_mov_b64_e32 v[66:67], 0
	v_mov_b64_e32 v[68:69], 0
	v_mov_b64_e32 v[70:71], 0
	v_mov_b64_e32 v[72:73], 0
	v_mov_b64_e32 v[74:75], 0
	v_mov_b64_e32 v[76:77], 0
	v_mov_b64_e32 v[78:79], 0
	v_mov_b64_e32 v[80:81], 0
	v_mov_b64_e32 v[82:83], 0
	v_mov_b64_e32 v[84:85], 0
	v_mov_b64_e32 v[86:87], 0
	v_mov_b64_e32 v[88:89], 0
	v_mov_b64_e32 v[90:91], 0
	v_mov_b64_e32 v[92:93], 0
	v_mov_b64_e32 v[94:95], 0
	v_mov_b64_e32 v[96:97], 0
	v_mov_b64_e32 v[98:99], 0
	v_mov_b64_e32 v[100:101], 0
	v_mov_b64_e32 v[102:103], 0
	v_mov_b64_e32 v[104:105], 0
	v_mov_b64_e32 v[106:107], 0
	v_mov_b64_e32 v[108:109], 0
	v_mov_b64_e32 v[110:111], 0
	v_mov_b64_e32 v[112:113], 0
	v_mov_b64_e32 v[114:115], 0
	v_mov_b64_e32 v[120:121], 0
	v_mov_b64_e32 v[122:123], 0
	v_mov_b64_e32 v[152:153], 0
	v_mov_b64_e32 v[154:155], 0
	v_mov_b64_e32 v[156:157], 0
	v_mov_b64_e32 v[158:159], 0
	v_mov_b64_e32 v[160:161], 0
	v_mov_b64_e32 v[162:163], 0
	s_branch .LBB0_455

;     __device__ __forceinline__ void prefetch(const Unit& u, PG8_LAS unsigned char* slot, int tid, int wid) const { if (f.on) xslot_fetch(f.st + 8 * (u.pm * BM), f.c1 + u.pn * BM, f.c2 + u.pn * BM, slot, tid, wid); }
;     __device__ __forceinline__ void prefetch(const Unit& u, PG8_LAS unsigned char* slot, int tid, int wid) const { xslot_fetch(f.st + 8 * (u.pm * BM), f.c1 + u.pn * BM, f.c2 + u.pn * BM, slot, tid, wid); }
;     __device__ __forceinline__ void prefetch(const Unit& u, PG8_LAS unsigned char* slot, int tid, int wid) const { if (st_prev) xslot_fetch(st_prev + 8 * (u.pm * BM), gp + u.pn * BM, bp + u.pn * BM, slot, tid, wid); }
; template <class Epi, class Sched, bool ALIGN_EPI = false, bool SP2 = false>
; __device__ __forceinline__ void gemm_phase(PG8_LAS unsigned char* lds, const Gemm g, const Sched& S, const Epi& E) {
;     ...
;         const bool has_next = S.next(ui + 1, nxt);
;         const char* nA = has_next ? (const char*)g.A + (size_t)nxt.pm * tstep : cA; const char* nB = has_next ? (const char*)g.Bt + (size_t)nxt.pn * tstep : cB;
;         for (int t = 0; t < nt; t += 2) {
;             const bool last = (t == nt - 2);
;             const char* a1 = cA + (size_t)(t + 1) * kstep;
;             const char* a2 = last ? nA : cA + (size_t)(t + 2) * kstep; const char* b2 = last ? nB : cB + (size_t)(t + 2) * kstep;
;             const char* a3 = a2 + kstep; const char* b3 = b2 + kstep;
;             if (last) E.preload(pre, cur, wr, wc, fr, fq);
;             if (last && has_next) { S.a_ready(nxt); E.prefetch(nxt, lds + XSLOT_OFF + ((ui + 1) & 1) * XSLOT_BYTES, tid, wid); }
;     ...
;         for (int a = 0; a < 2; ++a)
; #pragma unroll
;             for (int b = 0; b < 2; ++b)
; #pragma unroll
;                 for (int m = 0; m < 4; ++m)
; #pragma unroll
;                     for (int n = 0; n < 2; ++n) acc[a][b][m][n] = (f32x4){0.f, 0.f, 0.f, 0.f};
;         cur = nxt; cA = nA; cB = nB; ++ui;
.LBB0_511:
	s_ashr_i32 s23, s22, 31
	s_lshl_b64 s[24:25], s[22:23], 19
	v_readlane_b32 s26, v250, 4
	v_readlane_b32 s27, v250, 5
	s_add_u32 s24, s26, s24
	s_addc_u32 s25, s27, s25
	s_and_b64 s[26:27], exec, s[0:1]
	s_cselect_b32 s23, s3, s25
	s_cselect_b32 s57, s2, s24
	s_ashr_i32 s21, s20, 31
	s_lshl_b64 s[26:27], s[20:21], 19
	s_add_u32 s26, s4, s26
	s_addc_u32 s27, s5, s27
	s_and_b64 s[34:35], exec, s[0:1]
	s_cselect_b32 s21, s31, s27
	s_cselect_b32 s58, s30, s26
	s_bitcmp1_b32 s54, 0
	s_cselect_b32 s34, 0x2800, 0
	s_lshl_b32 s60, s20, 8
	s_add_i32 s59, s34, 0
	s_lshl_b32 s34, s22, 11
	s_ashr_i32 s61, s60, 31
	s_add_i32 s59, s59, 0x20000
	s_ashr_i32 s35, s34, 31
	s_or_b64 s[0:1], s[0:1], s[14:15]
	s_lshl_b64 s[60:61], s[60:61], 2
	v_lshl_add_u64 v[4:5], v[172:173], 0, s[60:61]
	v_lshl_add_u64 v[6:7], v[174:175], 0, s[60:61]
	s_movk_i32 s60, 0xfc00
	s_add_u32 s2, s2, 0x40080
	s_mov_b32 s61, -1
	s_addc_u32 s3, s3, 0
	v_lshl_add_u64 v[6:7], v[6:7], 0, s[60:61]
	s_add_u32 s60, s30, 0x100
	v_cndmask_b32_e64 v132, v6, v4, s[40:41]
	s_addc_u32 s61, s31, 0
	v_mov_b32_e32 v4, 0
	s_add_i32 s63, s59, s53
	v_cndmask_b32_e64 v133, v7, v5, s[40:41]
	s_mov_b32 s62, -2
	s_addk_i32 s63, 0x2000
	v_mov_b32_e32 v5, v4
	v_mov_b64_e32 v[6:7], 0
	v_mov_b64_e32 v[8:9], 0
	v_mov_b64_e32 v[10:11], 0
	v_mov_b64_e32 v[12:13], 0
	v_mov_b64_e32 v[14:15], 0
	v_mov_b64_e32 v[16:17], 0
	v_mov_b64_e32 v[18:19], 0
	v_mov_b64_e32 v[20:21], 0
	v_mov_b64_e32 v[22:23], 0
	v_mov_b64_e32 v[24:25], 0
	v_mov_b64_e32 v[26:27], 0
	v_mov_b64_e32 v[28:29], 0
	v_mov_b64_e32 v[30:31], 0
	v_mov_b64_e32 v[32:33], 0
	v_mov_b64_e32 v[34:35], 0
	v_mov_b64_e32 v[36:37], 0
	v_mov_b64_e32 v[38:39], 0
	v_mov_b64_e32 v[40:41], 0
	v_mov_b64_e32 v[42:43], 0
	v_mov_b64_e32 v[44:45], 0
	v_mov_b64_e32 v[46:47], 0
	v_mov_b64_e32 v[48:49], 0
	v_mov_b64_e32 v[50:51], 0
	v_mov_b64_e32 v[52:53], 0
	v_mov_b64_e32 v[54:55], 0
	v_mov_b64_e32 v[56:57], 0
	v_mov_b64_e32 v[58:59], 0
	v_mov_b64_e32 v[60:61], 0
	v_mov_b64_e32 v[62:63], 0
	v_mov_b64_e32 v[64:65], 0
	v_mov_b64_e32 v[66:67], 0
	v_mov_b64_e32 v[68:69], 0
	v_mov_b64_e32 v[70:71], 0
	v_mov_b64_e32 v[72:73], 0
	v_mov_b64_e32 v[74:75], 0
	v_mov_b64_e32 v[76:77], 0
	v_mov_b64_e32 v[78:79], 0
	v_mov_b64_e32 v[80:81], 0
	v_mov_b64_e32 v[82:83], 0
	v_mov_b64_e32 v[84:85], 0
	v_mov_b64_e32 v[86:87], 0
	v_mov_b64_e32 v[88:89], 0
	v_mov_b64_e32 v[90:91], 0
	v_mov_b64_e32 v[92:93], 0
	v_mov_b64_e32 v[94:95], 0
	v_mov_b64_e32 v[96:97], 0
	v_mov_b64_e32 v[98:99], 0
	v_mov_b64_e32 v[100:101], 0
	v_mov_b64_e32 v[102:103], 0
	v_mov_b64_e32 v[104:105], 0
	v_mov_b64_e32 v[106:107], 0
	v_mov_b64_e32 v[108:109], 0
	v_mov_b64_e32 v[110:111], 0
	v_mov_b64_e32 v[112:113], 0
	v_mov_b64_e32 v[114:115], 0
	v_mov_b64_e32 v[116:117], 0
	v_mov_b64_e32 v[118:119], 0
	v_mov_b64_e32 v[120:121], 0
	v_mov_b64_e32 v[122:123], 0
	v_mov_b64_e32 v[124:125], 0
	v_mov_b64_e32 v[126:127], 0
	v_mov_b64_e32 v[128:129], 0
	v_mov_b64_e32 v[130:131], 0
	v_lshl_add_u64 v[134:135], s[34:35], 2, v[170:171]
	s_branch .LBB0_513
